# v61 + the four GEMM K-loop heads aligned to 64 bytes (.p2align 6): code placement pin
# speedup vs baseline: 1.0275x; 1.0053x over previous
; template <class Epi, class Sched>
; __device__ __forceinline__ void gemm_phase(LAS unsigned char* lds, const Gemm g, const Sched& S, const Epi& E) {
;     ...
;         for (int t = 0; t < nt; t += 2) {
;     ...
; #pragma unroll
;         for (int a = 0; a < 2; ++a)
; #pragma unroll
;             for (int b = 0; b < 2; ++b)
; #pragma unroll
;                 for (int m = 0; m < 4; ++m)
; #pragma unroll
;                     for (int n = 0; n < 2; ++n) acc[a][b][m][n] = (f32x4){0.f, 0.f, 0.f, 0.f};
;         cur = nxt; cA = nA; cB = nB; ++ui;
.LBB0_129:
	s_andn2_b64 vcc, exec, s[40:41]
	v_mov_b64_e32 v[2:3], 0
	v_mov_b64_e32 v[4:5], 0
	v_mov_b64_e32 v[6:7], 0
	v_mov_b64_e32 v[8:9], 0
	v_mov_b64_e32 v[10:11], 0
	v_mov_b64_e32 v[12:13], 0
	v_mov_b64_e32 v[14:15], 0
	v_mov_b64_e32 v[16:17], 0
	v_mov_b64_e32 v[18:19], 0
	v_mov_b64_e32 v[20:21], 0
	v_mov_b64_e32 v[22:23], 0
	v_mov_b64_e32 v[24:25], 0
	v_mov_b64_e32 v[26:27], 0
	v_mov_b64_e32 v[28:29], 0
	v_mov_b64_e32 v[30:31], 0
	v_mov_b64_e32 v[32:33], 0
	v_mov_b64_e32 v[34:35], 0
	v_mov_b64_e32 v[36:37], 0
	v_mov_b64_e32 v[38:39], 0
	v_mov_b64_e32 v[40:41], 0
	v_mov_b64_e32 v[42:43], 0
	v_mov_b64_e32 v[44:45], 0
	v_mov_b64_e32 v[46:47], 0
	v_mov_b64_e32 v[48:49], 0
	v_mov_b64_e32 v[50:51], 0
	v_mov_b64_e32 v[52:53], 0
	v_mov_b64_e32 v[54:55], 0
	v_mov_b64_e32 v[56:57], 0
	v_mov_b64_e32 v[58:59], 0
	v_mov_b64_e32 v[60:61], 0
	v_mov_b64_e32 v[62:63], 0
	v_mov_b64_e32 v[64:65], 0
	v_mov_b64_e32 v[66:67], 0
	v_mov_b64_e32 v[68:69], 0
	v_mov_b64_e32 v[70:71], 0
	v_mov_b64_e32 v[72:73], 0
	v_mov_b64_e32 v[74:75], 0
	v_mov_b64_e32 v[76:77], 0
	v_mov_b64_e32 v[78:79], 0
	v_mov_b64_e32 v[80:81], 0
	v_mov_b64_e32 v[82:83], 0
	v_mov_b64_e32 v[84:85], 0
	v_mov_b64_e32 v[86:87], 0
	v_mov_b64_e32 v[88:89], 0
	v_mov_b64_e32 v[90:91], 0
	v_mov_b64_e32 v[92:93], 0
	v_mov_b64_e32 v[94:95], 0
	v_mov_b64_e32 v[96:97], 0
	v_mov_b64_e32 v[98:99], 0
	v_mov_b64_e32 v[100:101], 0
	v_mov_b64_e32 v[102:103], 0
	v_mov_b64_e32 v[104:105], 0
	v_mov_b64_e32 v[106:107], 0
	v_mov_b64_e32 v[108:109], 0
	v_mov_b64_e32 v[110:111], 0
	v_mov_b64_e32 v[112:113], 0
	v_mov_b64_e32 v[114:115], 0
	v_mov_b64_e32 v[116:117], 0
	v_mov_b64_e32 v[118:119], 0
	v_mov_b64_e32 v[120:121], 0
	v_mov_b64_e32 v[122:123], 0
	v_mov_b64_e32 v[124:125], 0
	v_mov_b64_e32 v[126:127], 0
	v_mov_b64_e32 v[128:129], 0
	s_cbranch_vccnz .LBB0_132
	s_add_u32 s9, s46, 0x100
	s_addc_u32 s36, s47, 0
	s_mov_b32 s50, 0
	s_mov_b64 s[46:47], 0
	.p2align	6

; template <class Epi, class Sched>
; __device__ __forceinline__ void gemm_phase(LAS unsigned char* lds, const Gemm g, const Sched& S, const Epi& E) {
;     ...
;         for (int t = 0; t < nt; t += 2) {
;     ...
; #pragma unroll
;         for (int a = 0; a < 2; ++a)
; #pragma unroll
;             for (int b = 0; b < 2; ++b)
; #pragma unroll
;                 for (int m = 0; m < 4; ++m)
; #pragma unroll
;                     for (int n = 0; n < 2; ++n) acc[a][b][m][n] = (f32x4){0.f, 0.f, 0.f, 0.f};
;         cur = nxt; cA = nA; cB = nB; ++ui;
.LBB0_416:
	s_andn2_b64 vcc, exec, s[42:43]
	v_mov_b64_e32 v[2:3], 0
	v_mov_b64_e32 v[4:5], 0
	v_mov_b64_e32 v[6:7], 0
	v_mov_b64_e32 v[8:9], 0
	v_mov_b64_e32 v[10:11], 0
	v_mov_b64_e32 v[12:13], 0
	v_mov_b64_e32 v[14:15], 0
	v_mov_b64_e32 v[16:17], 0
	v_mov_b64_e32 v[18:19], 0
	v_mov_b64_e32 v[20:21], 0
	v_mov_b64_e32 v[22:23], 0
	v_mov_b64_e32 v[24:25], 0
	v_mov_b64_e32 v[26:27], 0
	v_mov_b64_e32 v[28:29], 0
	v_mov_b64_e32 v[30:31], 0
	v_mov_b64_e32 v[32:33], 0
	v_mov_b64_e32 v[34:35], 0
	v_mov_b64_e32 v[36:37], 0
	v_mov_b64_e32 v[38:39], 0
	v_mov_b64_e32 v[40:41], 0
	v_mov_b64_e32 v[42:43], 0
	v_mov_b64_e32 v[44:45], 0
	v_mov_b64_e32 v[46:47], 0
	v_mov_b64_e32 v[48:49], 0
	v_mov_b64_e32 v[50:51], 0
	v_mov_b64_e32 v[52:53], 0
	v_mov_b64_e32 v[54:55], 0
	v_mov_b64_e32 v[56:57], 0
	v_mov_b64_e32 v[58:59], 0
	v_mov_b64_e32 v[60:61], 0
	v_mov_b64_e32 v[62:63], 0
	v_mov_b64_e32 v[64:65], 0
	v_mov_b64_e32 v[66:67], 0
	v_mov_b64_e32 v[68:69], 0
	v_mov_b64_e32 v[70:71], 0
	v_mov_b64_e32 v[72:73], 0
	v_mov_b64_e32 v[74:75], 0
	v_mov_b64_e32 v[76:77], 0
	v_mov_b64_e32 v[78:79], 0
	v_mov_b64_e32 v[80:81], 0
	v_mov_b64_e32 v[82:83], 0
	v_mov_b64_e32 v[84:85], 0
	v_mov_b64_e32 v[86:87], 0
	v_mov_b64_e32 v[88:89], 0
	v_mov_b64_e32 v[90:91], 0
	v_mov_b64_e32 v[92:93], 0
	v_mov_b64_e32 v[94:95], 0
	v_mov_b64_e32 v[96:97], 0
	v_mov_b64_e32 v[98:99], 0
	v_mov_b64_e32 v[100:101], 0
	v_mov_b64_e32 v[102:103], 0
	v_mov_b64_e32 v[104:105], 0
	v_mov_b64_e32 v[106:107], 0
	v_mov_b64_e32 v[108:109], 0
	v_mov_b64_e32 v[110:111], 0
	v_mov_b64_e32 v[112:113], 0
	v_mov_b64_e32 v[114:115], 0
	v_mov_b64_e32 v[116:117], 0
	v_mov_b64_e32 v[118:119], 0
	v_mov_b64_e32 v[120:121], 0
	v_mov_b64_e32 v[122:123], 0
	v_mov_b64_e32 v[124:125], 0
	v_mov_b64_e32 v[126:127], 0
	v_mov_b64_e32 v[128:129], 0
	s_cbranch_vccnz .LBB0_419
	s_add_u32 s9, s48, 0x100
	s_addc_u32 s36, s49, 0
	s_mov_b32 s52, 0
	s_mov_b64 s[48:49], 0
	.p2align	6
